# beta/alpha MFMA GEMV: next activation load issued right after the bf16 unpack (before the 8 MFMAs) on top of the v147 combination
# speedup vs baseline: 1.0028x; 1.0011x over previous
; __device__ __forceinline__ float bf2f(bfu h) { return __uint_as_float(((unsigned)h) << 16); }
; #define SHX(v, m) shx_((v), (m), lane)
; __device__ __forceinline__ int ptid_(int wave) { int l_; asm volatile("v_mbcnt_lo_u32_b32 %0, -1, 0\n\tv_mbcnt_hi_u32_b32 %0, -1, %0" : "=v"(l_)); return (wave << 6) | l_; }
; __device__ void ba_item(const Params& p, int L, int rp) {
;     ...
;   const float* wba = misc + MF_WBA + (L >> 1) * 8192;
;   const float* rowss = misc + MF_RSP + (L == 0 ? 0L : 2L * MTOK * 16);
;   int tid = ptid_(p.tid); asm volatile("" : "+v"(tid));
;   const int wid = tid >> 6, lane = tid & 63;
;   f32x4 wr_[8][4];
;   _Pragma("unroll") for (int j = 0; j < 8; ++j) _Pragma("unroll") for (int e4 = 0; e4 < 4; ++e4)
;     wr_[j][e4] = *(const f32x4*)(wba + j * 1024 + lane * 16 + e4 * 4);
;   for (int bt = 0; bt < 8; ++bt) {
;     bf16x8 h0[2], h1[2]; f32x4 ps[2][4];
;     _Pragma("unroll") for (int u = 0; u < 2; ++u) {
;       const int row = rp * 128 + wid * 16 + bt * 2 + u;
;       const bfu* hr = hb + (long)row * 1024 + lane * 16;
;       h0[u] = *(const bf16x8*)hr; h1[u] = *(const bf16x8*)(hr + 8);
;       _Pragma("unroll") for (int i = 0; i < 4; ++i) ps[u][i] = *(const f32x4*)(rowss + (long)row * 16 + i * 4);
;     }
;     _Pragma("unroll") for (int u = 0; u < 2; ++u) {
;       const int row = rp * 128 + wid * 16 + bt * 2 + u;
;       float hf[16];
;       _Pragma("unroll") for (int e = 0; e < 8; ++e) { hf[e] = bf2f((bfu)h0[u][e]); hf[8 + e] = bf2f((bfu)h1[u][e]); }
;       float a[8];
;       _Pragma("unroll") for (int j = 0; j < 8; ++j) {
;         float s = 0.f;
;         _Pragma("unroll") for (int e4 = 0; e4 < 4; ++e4) _Pragma("unroll") for (int e = 0; e < 4; ++e) s += hf[e4 * 4 + e] * wr_[j][e4][e];
;         _Pragma("unroll") for (int o = 32; o >= 1; o >>= 1) s += SHX(s, o);
;         a[j] = s;
;       }
.LBB0_612:
	s_cmpk_gt_i32 s18, 0x6ff
	s_mov_b64 s[0:1], -1
	s_cbranch_scc0 .LBB0_628
	v_mbcnt_lo_u32_b32 v0, -1, 0
	v_mbcnt_hi_u32_b32 v0, -1, v0
	s_waitcnt vmcnt(0) lgkmcnt(0)
	v_or_b32_e32 v144, s33, v0
	v_lshlrev_b32_e32 v150, 4, v144
	global_load_dwordx4 v[152:155], v150, s[26:27]
	v_add_u32_e32 v150, 0x2000, v150
	global_load_dwordx4 v[156:159], v150, s[26:27]
	v_add_u32_e32 v150, 0x2000, v150
	global_load_dwordx4 v[160:163], v150, s[26:27]
	v_add_u32_e32 v150, 0x2000, v150
	global_load_dwordx4 v[164:167], v150, s[26:27]
	s_barrier
	v_readlane_b32 s24, v254, 62
	v_readlane_b32 s25, v254, 63
	s_lshr_b32 s2, s33, 2
	s_add_i32 s2, s2, s20
	s_add_i32 s2, s2, 0xfffc8000
	v_and_b32_e32 v2, 15, v0
	v_lshrrev_b32_e32 v3, 4, v0
	v_and_b32_e32 v145, 0xff, v144
	v_lshrrev_b32_e32 v149, 3, v145
	v_lshlrev_b32_e32 v149, 10, v149
	v_bfe_u32 v146, v144, 1, 2
	v_lshl_or_b32 v149, v146, 8, v149
	v_lshrrev_b32_e32 v146, 8, v144
	v_lshl_or_b32 v149, v146, 5, v149
	v_and_b32_e32 v146, 1, v144
	v_lshl_or_b32 v149, v146, 4, v149
	v_add_u32_e32 v144, s2, v2
	v_lshlrev_b32_e32 v144, 11, v144
	v_lshl_add_u32 v144, v3, 4, v144
	v_mov_b32_e32 v145, 0
	v_lshl_add_u64 v[4:5], s[80:81], 0, v[144:145]
	v_and_b32_e32 v138, 7, v2
	v_lshlrev_b32_e32 v148, 5, v138
	v_lshl_or_b32 v148, v3, 8, v148
	v_lshl_add_u32 v144, v3, 2, s2
	v_lshlrev_b32_e32 v144, 6, v144
	v_lshl_add_u64 v[136:137], s[24:25], 0, v[144:145]
	v_max_u32_e32 v144, 4, v138
	v_add_u32_e32 v144, s19, v144
	v_lshlrev_b32_e32 v144, 2, v144
	v_readlane_b32 s92, v254, 0
	v_readlane_b32 s93, v254, 1
	v_readlane_b32 s94, v254, 2
	v_readlane_b32 s95, v254, 3
	v_readlane_b32 s0, v252, 18
	v_readlane_b32 s1, v252, 19
	v_lshl_add_u32 v146, v3, 2, s2
	v_lshlrev_b32_e32 v146, 5, v146
	v_lshl_add_u32 v146, v138, 2, v146
	v_mov_b32_e32 v147, 0
	v_lshl_add_u64 v[140:141], s[0:1], 0, v[146:147]
	global_load_dword v142, v144, s[94:95]
	global_load_dword v143, v144, s[92:93]
	global_load_dwordx4 v[72:75], v[136:137], off offset:0
	global_load_dwordx4 v[76:79], v[136:137], off offset:16
	global_load_dwordx4 v[80:83], v[136:137], off offset:32
	global_load_dwordx4 v[84:87], v[136:137], off offset:48
	global_load_dwordx4 v[88:91], v[136:137], off offset:64
	global_load_dwordx4 v[92:95], v[136:137], off offset:80
	global_load_dwordx4 v[96:99], v[136:137], off offset:96
	global_load_dwordx4 v[100:103], v[136:137], off offset:112
	global_load_dwordx4 v[104:107], v[136:137], off offset:128
	global_load_dwordx4 v[108:111], v[136:137], off offset:144
	global_load_dwordx4 v[112:115], v[136:137], off offset:160
	global_load_dwordx4 v[116:119], v[136:137], off offset:176
	global_load_dwordx4 v[120:123], v[136:137], off offset:192
	global_load_dwordx4 v[124:127], v[136:137], off offset:208
	global_load_dwordx4 v[128:131], v[136:137], off offset:224
	global_load_dwordx4 v[132:135], v[136:137], off offset:240
	v_mov_b32_e32 v8, 0
	v_mov_b32_e32 v9, 0
	v_mov_b32_e32 v10, 0
	v_mov_b32_e32 v11, 0
	v_mov_b32_e32 v12, 0
	v_mov_b32_e32 v13, 0
	v_mov_b32_e32 v14, 0
	v_mov_b32_e32 v15, 0
	global_load_dwordx4 v[16:19], v[4:5], off
	global_load_dwordx4 v[20:23], v[4:5], off offset:64
	global_load_dwordx4 v[24:27], v[4:5], off offset:128
	global_load_dwordx4 v[28:31], v[4:5], off offset:192
	global_load_dwordx4 v[32:35], v[4:5], off offset:256
	global_load_dwordx4 v[36:39], v[4:5], off offset:320
	global_load_dwordx4 v[40:43], v[4:5], off offset:384
	global_load_dwordx4 v[44:47], v[4:5], off offset:448
	s_waitcnt vmcnt(26)
	ds_write_b128 v149, v[152:155]
	ds_write_b128 v149, v[156:159] offset:64
	ds_write_b128 v149, v[160:163] offset:128
	ds_write_b128 v149, v[164:167] offset:192
	s_waitcnt lgkmcnt(0)
	s_barrier
	ds_read_b128 v[48:51], v148
	ds_read_b128 v[52:55], v148 offset:16
	ds_read_b128 v[56:59], v148 offset:1024
	ds_read_b128 v[60:63], v148 offset:1040
	s_waitcnt vmcnt(7)
	v_lshlrev_b32_e32 v64, 16, v16
	v_and_b32_e32 v65, 0xffff0000, v16
	v_lshlrev_b32_e32 v66, 16, v17
	v_and_b32_e32 v67, 0xffff0000, v17
	v_lshlrev_b32_e32 v68, 16, v18
	v_and_b32_e32 v69, 0xffff0000, v18
	v_lshlrev_b32_e32 v70, 16, v19
	v_and_b32_e32 v71, 0xffff0000, v19
	global_load_dwordx4 v[16:19], v[4:5], off offset:512
	s_waitcnt lgkmcnt(2)
	v_mfma_f32_16x16x4_f32 v[8:11], v64, v48, v[8:11]
	v_mfma_f32_16x16x4_f32 v[8:11], v65, v49, v[8:11]
	v_mfma_f32_16x16x4_f32 v[8:11], v66, v50, v[8:11]
	v_mfma_f32_16x16x4_f32 v[8:11], v67, v51, v[8:11]
	v_mfma_f32_16x16x4_f32 v[8:11], v68, v52, v[8:11]
	v_mfma_f32_16x16x4_f32 v[8:11], v69, v53, v[8:11]
	v_mfma_f32_16x16x4_f32 v[8:11], v70, v54, v[8:11]
	v_mfma_f32_16x16x4_f32 v[8:11], v71, v55, v[8:11]
	ds_read_b128 v[48:51], v148 offset:2048
	ds_read_b128 v[52:55], v148 offset:2064
	s_waitcnt vmcnt(7)
	v_lshlrev_b32_e32 v64, 16, v20
	v_and_b32_e32 v65, 0xffff0000, v20
	v_lshlrev_b32_e32 v66, 16, v21
	v_and_b32_e32 v67, 0xffff0000, v21
	v_lshlrev_b32_e32 v68, 16, v22
	v_and_b32_e32 v69, 0xffff0000, v22
	v_lshlrev_b32_e32 v70, 16, v23
	v_and_b32_e32 v71, 0xffff0000, v23
	global_load_dwordx4 v[20:23], v[4:5], off offset:576
	s_waitcnt lgkmcnt(2)
	v_mfma_f32_16x16x4_f32 v[8:11], v64, v56, v[8:11]
	v_mfma_f32_16x16x4_f32 v[8:11], v65, v57, v[8:11]
	v_mfma_f32_16x16x4_f32 v[8:11], v66, v58, v[8:11]
	v_mfma_f32_16x16x4_f32 v[8:11], v67, v59, v[8:11]
	v_mfma_f32_16x16x4_f32 v[8:11], v68, v60, v[8:11]
	v_mfma_f32_16x16x4_f32 v[8:11], v69, v61, v[8:11]
	v_mfma_f32_16x16x4_f32 v[8:11], v70, v62, v[8:11]
	v_mfma_f32_16x16x4_f32 v[8:11], v71, v63, v[8:11]
	ds_read_b128 v[56:59], v148 offset:3072
	ds_read_b128 v[60:63], v148 offset:3088
	s_waitcnt vmcnt(7)
; #define SHX(v, m) shx_((v), (m), lane)
; __device__ void ba_item(const Params& p, int L, int rp) {
;     ...
;       _Pragma("unroll") for (int j = 0; j < 8; ++j) {
;         float s = 0.f;
;         _Pragma("unroll") for (int e4 = 0; e4 < 4; ++e4) _Pragma("unroll") for (int e = 0; e < 4; ++e) s += hf[e4 * 4 + e] * wr_[j][e4][e];
;         _Pragma("unroll") for (int o = 32; o >= 1; o >>= 1) s += SHX(s, o);
;         a[j] = s;
;       }
	v_lshlrev_b32_e32 v64, 16, v24
	v_and_b32_e32 v65, 0xffff0000, v24
	v_lshlrev_b32_e32 v66, 16, v25
	v_and_b32_e32 v67, 0xffff0000, v25
	v_lshlrev_b32_e32 v68, 16, v26
	v_and_b32_e32 v69, 0xffff0000, v26
	v_lshlrev_b32_e32 v70, 16, v27
	v_and_b32_e32 v71, 0xffff0000, v27
	global_load_dwordx4 v[24:27], v[4:5], off offset:640
	s_waitcnt lgkmcnt(2)
	v_mfma_f32_16x16x4_f32 v[8:11], v64, v48, v[8:11]
	v_mfma_f32_16x16x4_f32 v[8:11], v65, v49, v[8:11]
	v_mfma_f32_16x16x4_f32 v[8:11], v66, v50, v[8:11]
	v_mfma_f32_16x16x4_f32 v[8:11], v67, v51, v[8:11]
	v_mfma_f32_16x16x4_f32 v[8:11], v68, v52, v[8:11]
	v_mfma_f32_16x16x4_f32 v[8:11], v69, v53, v[8:11]
	v_mfma_f32_16x16x4_f32 v[8:11], v70, v54, v[8:11]
	v_mfma_f32_16x16x4_f32 v[8:11], v71, v55, v[8:11]
	ds_read_b128 v[48:51], v148 offset:4096
	ds_read_b128 v[52:55], v148 offset:4112
	s_waitcnt vmcnt(7)
	v_lshlrev_b32_e32 v64, 16, v28
	v_and_b32_e32 v65, 0xffff0000, v28
	v_lshlrev_b32_e32 v66, 16, v29
	v_and_b32_e32 v67, 0xffff0000, v29
	v_lshlrev_b32_e32 v68, 16, v30
	v_and_b32_e32 v69, 0xffff0000, v30
	v_lshlrev_b32_e32 v70, 16, v31
	v_and_b32_e32 v71, 0xffff0000, v31
	global_load_dwordx4 v[28:31], v[4:5], off offset:704
	s_waitcnt lgkmcnt(2)
	v_mfma_f32_16x16x4_f32 v[8:11], v64, v56, v[8:11]
	v_mfma_f32_16x16x4_f32 v[8:11], v65, v57, v[8:11]
	v_mfma_f32_16x16x4_f32 v[8:11], v66, v58, v[8:11]
	v_mfma_f32_16x16x4_f32 v[8:11], v67, v59, v[8:11]
	v_mfma_f32_16x16x4_f32 v[8:11], v68, v60, v[8:11]
	v_mfma_f32_16x16x4_f32 v[8:11], v69, v61, v[8:11]
	v_mfma_f32_16x16x4_f32 v[8:11], v70, v62, v[8:11]
	v_mfma_f32_16x16x4_f32 v[8:11], v71, v63, v[8:11]
	ds_read_b128 v[56:59], v148 offset:5120
	ds_read_b128 v[60:63], v148 offset:5136
	s_waitcnt vmcnt(7)
	v_lshlrev_b32_e32 v64, 16, v32
	v_and_b32_e32 v65, 0xffff0000, v32
	v_lshlrev_b32_e32 v66, 16, v33
	v_and_b32_e32 v67, 0xffff0000, v33
	v_lshlrev_b32_e32 v68, 16, v34
	v_and_b32_e32 v69, 0xffff0000, v34
	v_lshlrev_b32_e32 v70, 16, v35
	v_and_b32_e32 v71, 0xffff0000, v35
	global_load_dwordx4 v[32:35], v[4:5], off offset:768
	s_waitcnt lgkmcnt(2)
	v_mfma_f32_16x16x4_f32 v[8:11], v64, v48, v[8:11]
	v_mfma_f32_16x16x4_f32 v[8:11], v65, v49, v[8:11]
	v_mfma_f32_16x16x4_f32 v[8:11], v66, v50, v[8:11]
	v_mfma_f32_16x16x4_f32 v[8:11], v67, v51, v[8:11]
	v_mfma_f32_16x16x4_f32 v[8:11], v68, v52, v[8:11]
	v_mfma_f32_16x16x4_f32 v[8:11], v69, v53, v[8:11]
	v_mfma_f32_16x16x4_f32 v[8:11], v70, v54, v[8:11]
	v_mfma_f32_16x16x4_f32 v[8:11], v71, v55, v[8:11]
	ds_read_b128 v[48:51], v148 offset:6144
	ds_read_b128 v[52:55], v148 offset:6160
	s_waitcnt vmcnt(7)
	v_lshlrev_b32_e32 v64, 16, v36
	v_and_b32_e32 v65, 0xffff0000, v36
	v_lshlrev_b32_e32 v66, 16, v37
	v_and_b32_e32 v67, 0xffff0000, v37
	v_lshlrev_b32_e32 v68, 16, v38
	v_and_b32_e32 v69, 0xffff0000, v38
	v_lshlrev_b32_e32 v70, 16, v39
	v_and_b32_e32 v71, 0xffff0000, v39
	global_load_dwordx4 v[36:39], v[4:5], off offset:832
	s_waitcnt lgkmcnt(2)
	v_mfma_f32_16x16x4_f32 v[8:11], v64, v56, v[8:11]
	v_mfma_f32_16x16x4_f32 v[8:11], v65, v57, v[8:11]
	v_mfma_f32_16x16x4_f32 v[8:11], v66, v58, v[8:11]
	v_mfma_f32_16x16x4_f32 v[8:11], v67, v59, v[8:11]
	v_mfma_f32_16x16x4_f32 v[8:11], v68, v60, v[8:11]
	v_mfma_f32_16x16x4_f32 v[8:11], v69, v61, v[8:11]
	v_mfma_f32_16x16x4_f32 v[8:11], v70, v62, v[8:11]
	v_mfma_f32_16x16x4_f32 v[8:11], v71, v63, v[8:11]
	ds_read_b128 v[56:59], v148 offset:7168
	ds_read_b128 v[60:63], v148 offset:7184
	s_waitcnt vmcnt(7)
	v_lshlrev_b32_e32 v64, 16, v40
	v_and_b32_e32 v65, 0xffff0000, v40
	v_lshlrev_b32_e32 v66, 16, v41
	v_and_b32_e32 v67, 0xffff0000, v41
	v_lshlrev_b32_e32 v68, 16, v42
	v_and_b32_e32 v69, 0xffff0000, v42
	v_lshlrev_b32_e32 v70, 16, v43
	v_and_b32_e32 v71, 0xffff0000, v43
	global_load_dwordx4 v[40:43], v[4:5], off offset:896
	s_waitcnt lgkmcnt(2)
	v_mfma_f32_16x16x4_f32 v[8:11], v64, v48, v[8:11]
	v_mfma_f32_16x16x4_f32 v[8:11], v65, v49, v[8:11]
	v_mfma_f32_16x16x4_f32 v[8:11], v66, v50, v[8:11]
	v_mfma_f32_16x16x4_f32 v[8:11], v67, v51, v[8:11]
	v_mfma_f32_16x16x4_f32 v[8:11], v68, v52, v[8:11]
	v_mfma_f32_16x16x4_f32 v[8:11], v69, v53, v[8:11]
	v_mfma_f32_16x16x4_f32 v[8:11], v70, v54, v[8:11]
	v_mfma_f32_16x16x4_f32 v[8:11], v71, v55, v[8:11]
	ds_read_b128 v[48:51], v148 offset:8192
	ds_read_b128 v[52:55], v148 offset:8208
	s_waitcnt vmcnt(7)
	v_lshlrev_b32_e32 v64, 16, v44
	v_and_b32_e32 v65, 0xffff0000, v44
	v_lshlrev_b32_e32 v66, 16, v45
	v_and_b32_e32 v67, 0xffff0000, v45
	v_lshlrev_b32_e32 v68, 16, v46
	v_and_b32_e32 v69, 0xffff0000, v46
	v_lshlrev_b32_e32 v70, 16, v47
	v_and_b32_e32 v71, 0xffff0000, v47
	global_load_dwordx4 v[44:47], v[4:5], off offset:960
	s_waitcnt lgkmcnt(2)
	v_mfma_f32_16x16x4_f32 v[8:11], v64, v56, v[8:11]
	v_mfma_f32_16x16x4_f32 v[8:11], v65, v57, v[8:11]
	v_mfma_f32_16x16x4_f32 v[8:11], v66, v58, v[8:11]
	v_mfma_f32_16x16x4_f32 v[8:11], v67, v59, v[8:11]
	v_mfma_f32_16x16x4_f32 v[8:11], v68, v60, v[8:11]
	v_mfma_f32_16x16x4_f32 v[8:11], v69, v61, v[8:11]
	v_mfma_f32_16x16x4_f32 v[8:11], v70, v62, v[8:11]
	v_mfma_f32_16x16x4_f32 v[8:11], v71, v63, v[8:11]
	ds_read_b128 v[56:59], v148 offset:9216
	ds_read_b128 v[60:63], v148 offset:9232
	s_waitcnt vmcnt(7)
	v_lshlrev_b32_e32 v64, 16, v16
	v_and_b32_e32 v65, 0xffff0000, v16
	v_lshlrev_b32_e32 v66, 16, v17
	v_and_b32_e32 v67, 0xffff0000, v17
	v_lshlrev_b32_e32 v68, 16, v18
	v_and_b32_e32 v69, 0xffff0000, v18
	v_lshlrev_b32_e32 v70, 16, v19
	v_and_b32_e32 v71, 0xffff0000, v19
	global_load_dwordx4 v[16:19], v[4:5], off offset:1024
	s_waitcnt lgkmcnt(2)
; #define SHX(v, m) shx_((v), (m), lane)
; __device__ void ba_item(const Params& p, int L, int rp) {
;     ...
;       _Pragma("unroll") for (int j = 0; j < 8; ++j) {
;         float s = 0.f;
;         _Pragma("unroll") for (int e4 = 0; e4 < 4; ++e4) _Pragma("unroll") for (int e = 0; e < 4; ++e) s += hf[e4 * 4 + e] * wr_[j][e4][e];
;         _Pragma("unroll") for (int o = 32; o >= 1; o >>= 1) s += SHX(s, o);
;         a[j] = s;
;       }
	v_mfma_f32_16x16x4_f32 v[8:11], v64, v48, v[8:11]
	v_mfma_f32_16x16x4_f32 v[8:11], v65, v49, v[8:11]
	v_mfma_f32_16x16x4_f32 v[8:11], v66, v50, v[8:11]
	v_mfma_f32_16x16x4_f32 v[8:11], v67, v51, v[8:11]
	v_mfma_f32_16x16x4_f32 v[8:11], v68, v52, v[8:11]
	v_mfma_f32_16x16x4_f32 v[8:11], v69, v53, v[8:11]
	v_mfma_f32_16x16x4_f32 v[8:11], v70, v54, v[8:11]
	v_mfma_f32_16x16x4_f32 v[8:11], v71, v55, v[8:11]
	ds_read_b128 v[48:51], v148 offset:10240
	ds_read_b128 v[52:55], v148 offset:10256
	s_waitcnt vmcnt(7)
	v_lshlrev_b32_e32 v64, 16, v20
	v_and_b32_e32 v65, 0xffff0000, v20
	v_lshlrev_b32_e32 v66, 16, v21
	v_and_b32_e32 v67, 0xffff0000, v21
	v_lshlrev_b32_e32 v68, 16, v22
	v_and_b32_e32 v69, 0xffff0000, v22
	v_lshlrev_b32_e32 v70, 16, v23
	v_and_b32_e32 v71, 0xffff0000, v23
	global_load_dwordx4 v[20:23], v[4:5], off offset:1088
	s_waitcnt lgkmcnt(2)
	v_mfma_f32_16x16x4_f32 v[8:11], v64, v56, v[8:11]
	v_mfma_f32_16x16x4_f32 v[8:11], v65, v57, v[8:11]
	v_mfma_f32_16x16x4_f32 v[8:11], v66, v58, v[8:11]
	v_mfma_f32_16x16x4_f32 v[8:11], v67, v59, v[8:11]
	v_mfma_f32_16x16x4_f32 v[8:11], v68, v60, v[8:11]
	v_mfma_f32_16x16x4_f32 v[8:11], v69, v61, v[8:11]
	v_mfma_f32_16x16x4_f32 v[8:11], v70, v62, v[8:11]
	v_mfma_f32_16x16x4_f32 v[8:11], v71, v63, v[8:11]
	ds_read_b128 v[56:59], v148 offset:11264
	ds_read_b128 v[60:63], v148 offset:11280
	s_waitcnt vmcnt(7)
	v_lshlrev_b32_e32 v64, 16, v24
	v_and_b32_e32 v65, 0xffff0000, v24
	v_lshlrev_b32_e32 v66, 16, v25
	v_and_b32_e32 v67, 0xffff0000, v25
	v_lshlrev_b32_e32 v68, 16, v26
	v_and_b32_e32 v69, 0xffff0000, v26
	v_lshlrev_b32_e32 v70, 16, v27
	v_and_b32_e32 v71, 0xffff0000, v27
	global_load_dwordx4 v[24:27], v[4:5], off offset:1152
	s_waitcnt lgkmcnt(2)
	v_mfma_f32_16x16x4_f32 v[8:11], v64, v48, v[8:11]
	v_mfma_f32_16x16x4_f32 v[8:11], v65, v49, v[8:11]
	v_mfma_f32_16x16x4_f32 v[8:11], v66, v50, v[8:11]
	v_mfma_f32_16x16x4_f32 v[8:11], v67, v51, v[8:11]
	v_mfma_f32_16x16x4_f32 v[8:11], v68, v52, v[8:11]
	v_mfma_f32_16x16x4_f32 v[8:11], v69, v53, v[8:11]
	v_mfma_f32_16x16x4_f32 v[8:11], v70, v54, v[8:11]
	v_mfma_f32_16x16x4_f32 v[8:11], v71, v55, v[8:11]
	ds_read_b128 v[48:51], v148 offset:12288
	ds_read_b128 v[52:55], v148 offset:12304
	s_waitcnt vmcnt(7)
	v_lshlrev_b32_e32 v64, 16, v28
	v_and_b32_e32 v65, 0xffff0000, v28
	v_lshlrev_b32_e32 v66, 16, v29
	v_and_b32_e32 v67, 0xffff0000, v29
	v_lshlrev_b32_e32 v68, 16, v30
	v_and_b32_e32 v69, 0xffff0000, v30
	v_lshlrev_b32_e32 v70, 16, v31
	v_and_b32_e32 v71, 0xffff0000, v31
	global_load_dwordx4 v[28:31], v[4:5], off offset:1216
	s_waitcnt lgkmcnt(2)
	v_mfma_f32_16x16x4_f32 v[8:11], v64, v56, v[8:11]
	v_mfma_f32_16x16x4_f32 v[8:11], v65, v57, v[8:11]
	v_mfma_f32_16x16x4_f32 v[8:11], v66, v58, v[8:11]
	v_mfma_f32_16x16x4_f32 v[8:11], v67, v59, v[8:11]
	v_mfma_f32_16x16x4_f32 v[8:11], v68, v60, v[8:11]
	v_mfma_f32_16x16x4_f32 v[8:11], v69, v61, v[8:11]
	v_mfma_f32_16x16x4_f32 v[8:11], v70, v62, v[8:11]
	v_mfma_f32_16x16x4_f32 v[8:11], v71, v63, v[8:11]
	ds_read_b128 v[56:59], v148 offset:13312
	ds_read_b128 v[60:63], v148 offset:13328
	s_waitcnt vmcnt(7)
	v_lshlrev_b32_e32 v64, 16, v32
	v_and_b32_e32 v65, 0xffff0000, v32
	v_lshlrev_b32_e32 v66, 16, v33
	v_and_b32_e32 v67, 0xffff0000, v33
	v_lshlrev_b32_e32 v68, 16, v34
	v_and_b32_e32 v69, 0xffff0000, v34
	v_lshlrev_b32_e32 v70, 16, v35
	v_and_b32_e32 v71, 0xffff0000, v35
	global_load_dwordx4 v[32:35], v[4:5], off offset:1280
	s_waitcnt lgkmcnt(2)
	v_mfma_f32_16x16x4_f32 v[8:11], v64, v48, v[8:11]
	v_mfma_f32_16x16x4_f32 v[8:11], v65, v49, v[8:11]
	v_mfma_f32_16x16x4_f32 v[8:11], v66, v50, v[8:11]
	v_mfma_f32_16x16x4_f32 v[8:11], v67, v51, v[8:11]
	v_mfma_f32_16x16x4_f32 v[8:11], v68, v52, v[8:11]
	v_mfma_f32_16x16x4_f32 v[8:11], v69, v53, v[8:11]
	v_mfma_f32_16x16x4_f32 v[8:11], v70, v54, v[8:11]
	v_mfma_f32_16x16x4_f32 v[8:11], v71, v55, v[8:11]
	ds_read_b128 v[48:51], v148 offset:14336
	ds_read_b128 v[52:55], v148 offset:14352
	s_waitcnt vmcnt(7)
	v_lshlrev_b32_e32 v64, 16, v36
	v_and_b32_e32 v65, 0xffff0000, v36
	v_lshlrev_b32_e32 v66, 16, v37
	v_and_b32_e32 v67, 0xffff0000, v37
	v_lshlrev_b32_e32 v68, 16, v38
	v_and_b32_e32 v69, 0xffff0000, v38
	v_lshlrev_b32_e32 v70, 16, v39
	v_and_b32_e32 v71, 0xffff0000, v39
	global_load_dwordx4 v[36:39], v[4:5], off offset:1344
	s_waitcnt lgkmcnt(2)
	v_mfma_f32_16x16x4_f32 v[8:11], v64, v56, v[8:11]
	v_mfma_f32_16x16x4_f32 v[8:11], v65, v57, v[8:11]
	v_mfma_f32_16x16x4_f32 v[8:11], v66, v58, v[8:11]
	v_mfma_f32_16x16x4_f32 v[8:11], v67, v59, v[8:11]
	v_mfma_f32_16x16x4_f32 v[8:11], v68, v60, v[8:11]
	v_mfma_f32_16x16x4_f32 v[8:11], v69, v61, v[8:11]
	v_mfma_f32_16x16x4_f32 v[8:11], v70, v62, v[8:11]
	v_mfma_f32_16x16x4_f32 v[8:11], v71, v63, v[8:11]
	ds_read_b128 v[56:59], v148 offset:15360
	ds_read_b128 v[60:63], v148 offset:15376
	s_waitcnt vmcnt(7)
	v_lshlrev_b32_e32 v64, 16, v40
	v_and_b32_e32 v65, 0xffff0000, v40
	v_lshlrev_b32_e32 v66, 16, v41
	v_and_b32_e32 v67, 0xffff0000, v41
	v_lshlrev_b32_e32 v68, 16, v42
	v_and_b32_e32 v69, 0xffff0000, v42
	v_lshlrev_b32_e32 v70, 16, v43
	v_and_b32_e32 v71, 0xffff0000, v43
	global_load_dwordx4 v[40:43], v[4:5], off offset:1408
	s_waitcnt lgkmcnt(2)
	v_mfma_f32_16x16x4_f32 v[8:11], v64, v48, v[8:11]
	v_mfma_f32_16x16x4_f32 v[8:11], v65, v49, v[8:11]
	v_mfma_f32_16x16x4_f32 v[8:11], v66, v50, v[8:11]
	v_mfma_f32_16x16x4_f32 v[8:11], v67, v51, v[8:11]
	v_mfma_f32_16x16x4_f32 v[8:11], v68, v52, v[8:11]
	v_mfma_f32_16x16x4_f32 v[8:11], v69, v53, v[8:11]
	v_mfma_f32_16x16x4_f32 v[8:11], v70, v54, v[8:11]
	v_mfma_f32_16x16x4_f32 v[8:11], v71, v55, v[8:11]
	ds_read_b128 v[48:51], v148 offset:16384
	ds_read_b128 v[52:55], v148 offset:16400
	s_waitcnt vmcnt(7)
; #define SHX(v, m) shx_((v), (m), lane)
; __device__ void ba_item(const Params& p, int L, int rp) {
;     ...
;       _Pragma("unroll") for (int j = 0; j < 8; ++j) {
;         float s = 0.f;
;         _Pragma("unroll") for (int e4 = 0; e4 < 4; ++e4) _Pragma("unroll") for (int e = 0; e < 4; ++e) s += hf[e4 * 4 + e] * wr_[j][e4][e];
;         _Pragma("unroll") for (int o = 32; o >= 1; o >>= 1) s += SHX(s, o);
;         a[j] = s;
;       }
	v_lshlrev_b32_e32 v64, 16, v44
	v_and_b32_e32 v65, 0xffff0000, v44
	v_lshlrev_b32_e32 v66, 16, v45
	v_and_b32_e32 v67, 0xffff0000, v45
	v_lshlrev_b32_e32 v68, 16, v46
	v_and_b32_e32 v69, 0xffff0000, v46
	v_lshlrev_b32_e32 v70, 16, v47
	v_and_b32_e32 v71, 0xffff0000, v47
	global_load_dwordx4 v[44:47], v[4:5], off offset:1472
	s_waitcnt lgkmcnt(2)
	v_mfma_f32_16x16x4_f32 v[8:11], v64, v56, v[8:11]
	v_mfma_f32_16x16x4_f32 v[8:11], v65, v57, v[8:11]
	v_mfma_f32_16x16x4_f32 v[8:11], v66, v58, v[8:11]
	v_mfma_f32_16x16x4_f32 v[8:11], v67, v59, v[8:11]
	v_mfma_f32_16x16x4_f32 v[8:11], v68, v60, v[8:11]
	v_mfma_f32_16x16x4_f32 v[8:11], v69, v61, v[8:11]
	v_mfma_f32_16x16x4_f32 v[8:11], v70, v62, v[8:11]
	v_mfma_f32_16x16x4_f32 v[8:11], v71, v63, v[8:11]
	ds_read_b128 v[56:59], v148 offset:17408
	ds_read_b128 v[60:63], v148 offset:17424
	s_waitcnt vmcnt(7)
	v_lshlrev_b32_e32 v64, 16, v16
	v_and_b32_e32 v65, 0xffff0000, v16
	v_lshlrev_b32_e32 v66, 16, v17
	v_and_b32_e32 v67, 0xffff0000, v17
	v_lshlrev_b32_e32 v68, 16, v18
	v_and_b32_e32 v69, 0xffff0000, v18
	v_lshlrev_b32_e32 v70, 16, v19
	v_and_b32_e32 v71, 0xffff0000, v19
	global_load_dwordx4 v[16:19], v[4:5], off offset:1536
	s_waitcnt lgkmcnt(2)
	v_mfma_f32_16x16x4_f32 v[8:11], v64, v48, v[8:11]
	v_mfma_f32_16x16x4_f32 v[8:11], v65, v49, v[8:11]
	v_mfma_f32_16x16x4_f32 v[8:11], v66, v50, v[8:11]
	v_mfma_f32_16x16x4_f32 v[8:11], v67, v51, v[8:11]
	v_mfma_f32_16x16x4_f32 v[8:11], v68, v52, v[8:11]
	v_mfma_f32_16x16x4_f32 v[8:11], v69, v53, v[8:11]
	v_mfma_f32_16x16x4_f32 v[8:11], v70, v54, v[8:11]
	v_mfma_f32_16x16x4_f32 v[8:11], v71, v55, v[8:11]
	ds_read_b128 v[48:51], v148 offset:18432
	ds_read_b128 v[52:55], v148 offset:18448
	s_waitcnt vmcnt(7)
	v_lshlrev_b32_e32 v64, 16, v20
	v_and_b32_e32 v65, 0xffff0000, v20
	v_lshlrev_b32_e32 v66, 16, v21
	v_and_b32_e32 v67, 0xffff0000, v21
	v_lshlrev_b32_e32 v68, 16, v22
	v_and_b32_e32 v69, 0xffff0000, v22
	v_lshlrev_b32_e32 v70, 16, v23
	v_and_b32_e32 v71, 0xffff0000, v23
	global_load_dwordx4 v[20:23], v[4:5], off offset:1600
	s_waitcnt lgkmcnt(2)
	v_mfma_f32_16x16x4_f32 v[8:11], v64, v56, v[8:11]
	v_mfma_f32_16x16x4_f32 v[8:11], v65, v57, v[8:11]
	v_mfma_f32_16x16x4_f32 v[8:11], v66, v58, v[8:11]
	v_mfma_f32_16x16x4_f32 v[8:11], v67, v59, v[8:11]
	v_mfma_f32_16x16x4_f32 v[8:11], v68, v60, v[8:11]
	v_mfma_f32_16x16x4_f32 v[8:11], v69, v61, v[8:11]
	v_mfma_f32_16x16x4_f32 v[8:11], v70, v62, v[8:11]
	v_mfma_f32_16x16x4_f32 v[8:11], v71, v63, v[8:11]
	ds_read_b128 v[56:59], v148 offset:19456
	ds_read_b128 v[60:63], v148 offset:19472
	s_waitcnt vmcnt(7)
	v_lshlrev_b32_e32 v64, 16, v24
	v_and_b32_e32 v65, 0xffff0000, v24
	v_lshlrev_b32_e32 v66, 16, v25
	v_and_b32_e32 v67, 0xffff0000, v25
	v_lshlrev_b32_e32 v68, 16, v26
	v_and_b32_e32 v69, 0xffff0000, v26
	v_lshlrev_b32_e32 v70, 16, v27
	v_and_b32_e32 v71, 0xffff0000, v27
	global_load_dwordx4 v[24:27], v[4:5], off offset:1664
	s_waitcnt lgkmcnt(2)
	v_mfma_f32_16x16x4_f32 v[8:11], v64, v48, v[8:11]
	v_mfma_f32_16x16x4_f32 v[8:11], v65, v49, v[8:11]
	v_mfma_f32_16x16x4_f32 v[8:11], v66, v50, v[8:11]
	v_mfma_f32_16x16x4_f32 v[8:11], v67, v51, v[8:11]
	v_mfma_f32_16x16x4_f32 v[8:11], v68, v52, v[8:11]
	v_mfma_f32_16x16x4_f32 v[8:11], v69, v53, v[8:11]
	v_mfma_f32_16x16x4_f32 v[8:11], v70, v54, v[8:11]
	v_mfma_f32_16x16x4_f32 v[8:11], v71, v55, v[8:11]
	ds_read_b128 v[48:51], v148 offset:20480
	ds_read_b128 v[52:55], v148 offset:20496
	s_waitcnt vmcnt(7)
	v_lshlrev_b32_e32 v64, 16, v28
	v_and_b32_e32 v65, 0xffff0000, v28
	v_lshlrev_b32_e32 v66, 16, v29
	v_and_b32_e32 v67, 0xffff0000, v29
	v_lshlrev_b32_e32 v68, 16, v30
	v_and_b32_e32 v69, 0xffff0000, v30
	v_lshlrev_b32_e32 v70, 16, v31
	v_and_b32_e32 v71, 0xffff0000, v31
	global_load_dwordx4 v[28:31], v[4:5], off offset:1728
	s_waitcnt lgkmcnt(2)
	v_mfma_f32_16x16x4_f32 v[8:11], v64, v56, v[8:11]
	v_mfma_f32_16x16x4_f32 v[8:11], v65, v57, v[8:11]
	v_mfma_f32_16x16x4_f32 v[8:11], v66, v58, v[8:11]
	v_mfma_f32_16x16x4_f32 v[8:11], v67, v59, v[8:11]
	v_mfma_f32_16x16x4_f32 v[8:11], v68, v60, v[8:11]
	v_mfma_f32_16x16x4_f32 v[8:11], v69, v61, v[8:11]
	v_mfma_f32_16x16x4_f32 v[8:11], v70, v62, v[8:11]
	v_mfma_f32_16x16x4_f32 v[8:11], v71, v63, v[8:11]
	ds_read_b128 v[56:59], v148 offset:21504
	ds_read_b128 v[60:63], v148 offset:21520
	s_waitcnt vmcnt(7)
	v_lshlrev_b32_e32 v64, 16, v32
	v_and_b32_e32 v65, 0xffff0000, v32
	v_lshlrev_b32_e32 v66, 16, v33
	v_and_b32_e32 v67, 0xffff0000, v33
	v_lshlrev_b32_e32 v68, 16, v34
	v_and_b32_e32 v69, 0xffff0000, v34
	v_lshlrev_b32_e32 v70, 16, v35
	v_and_b32_e32 v71, 0xffff0000, v35
	global_load_dwordx4 v[32:35], v[4:5], off offset:1792
	s_waitcnt lgkmcnt(2)
	v_mfma_f32_16x16x4_f32 v[8:11], v64, v48, v[8:11]
	v_mfma_f32_16x16x4_f32 v[8:11], v65, v49, v[8:11]
	v_mfma_f32_16x16x4_f32 v[8:11], v66, v50, v[8:11]
	v_mfma_f32_16x16x4_f32 v[8:11], v67, v51, v[8:11]
	v_mfma_f32_16x16x4_f32 v[8:11], v68, v52, v[8:11]
	v_mfma_f32_16x16x4_f32 v[8:11], v69, v53, v[8:11]
	v_mfma_f32_16x16x4_f32 v[8:11], v70, v54, v[8:11]
	v_mfma_f32_16x16x4_f32 v[8:11], v71, v55, v[8:11]
	ds_read_b128 v[48:51], v148 offset:22528
	ds_read_b128 v[52:55], v148 offset:22544
	s_waitcnt vmcnt(7)
	v_lshlrev_b32_e32 v64, 16, v36
	v_and_b32_e32 v65, 0xffff0000, v36
	v_lshlrev_b32_e32 v66, 16, v37
	v_and_b32_e32 v67, 0xffff0000, v37
	v_lshlrev_b32_e32 v68, 16, v38
	v_and_b32_e32 v69, 0xffff0000, v38
	v_lshlrev_b32_e32 v70, 16, v39
	v_and_b32_e32 v71, 0xffff0000, v39
	global_load_dwordx4 v[36:39], v[4:5], off offset:1856
	s_waitcnt lgkmcnt(2)
; #define SHX(v, m) shx_((v), (m), lane)
; __device__ void ba_item(const Params& p, int L, int rp) {
;     ...
;       _Pragma("unroll") for (int j = 0; j < 8; ++j) {
;         float s = 0.f;
;         _Pragma("unroll") for (int e4 = 0; e4 < 4; ++e4) _Pragma("unroll") for (int e = 0; e < 4; ++e) s += hf[e4 * 4 + e] * wr_[j][e4][e];
;         _Pragma("unroll") for (int o = 32; o >= 1; o >>= 1) s += SHX(s, o);
;         a[j] = s;
;       }
	v_mfma_f32_16x16x4_f32 v[8:11], v64, v56, v[8:11]
	v_mfma_f32_16x16x4_f32 v[8:11], v65, v57, v[8:11]
	v_mfma_f32_16x16x4_f32 v[8:11], v66, v58, v[8:11]
	v_mfma_f32_16x16x4_f32 v[8:11], v67, v59, v[8:11]
	v_mfma_f32_16x16x4_f32 v[8:11], v68, v60, v[8:11]
	v_mfma_f32_16x16x4_f32 v[8:11], v69, v61, v[8:11]
	v_mfma_f32_16x16x4_f32 v[8:11], v70, v62, v[8:11]
	v_mfma_f32_16x16x4_f32 v[8:11], v71, v63, v[8:11]
	ds_read_b128 v[56:59], v148 offset:23552
	ds_read_b128 v[60:63], v148 offset:23568
	s_waitcnt vmcnt(7)
	v_lshlrev_b32_e32 v64, 16, v40
	v_and_b32_e32 v65, 0xffff0000, v40
	v_lshlrev_b32_e32 v66, 16, v41
	v_and_b32_e32 v67, 0xffff0000, v41
	v_lshlrev_b32_e32 v68, 16, v42
	v_and_b32_e32 v69, 0xffff0000, v42
	v_lshlrev_b32_e32 v70, 16, v43
	v_and_b32_e32 v71, 0xffff0000, v43
	global_load_dwordx4 v[40:43], v[4:5], off offset:1920
	s_waitcnt lgkmcnt(2)
	v_mfma_f32_16x16x4_f32 v[8:11], v64, v48, v[8:11]
	v_mfma_f32_16x16x4_f32 v[8:11], v65, v49, v[8:11]
	v_mfma_f32_16x16x4_f32 v[8:11], v66, v50, v[8:11]
	v_mfma_f32_16x16x4_f32 v[8:11], v67, v51, v[8:11]
	v_mfma_f32_16x16x4_f32 v[8:11], v68, v52, v[8:11]
	v_mfma_f32_16x16x4_f32 v[8:11], v69, v53, v[8:11]
	v_mfma_f32_16x16x4_f32 v[8:11], v70, v54, v[8:11]
	v_mfma_f32_16x16x4_f32 v[8:11], v71, v55, v[8:11]
	ds_read_b128 v[48:51], v148 offset:24576
	ds_read_b128 v[52:55], v148 offset:24592
	s_waitcnt vmcnt(7)
	v_lshlrev_b32_e32 v64, 16, v44
	v_and_b32_e32 v65, 0xffff0000, v44
	v_lshlrev_b32_e32 v66, 16, v45
	v_and_b32_e32 v67, 0xffff0000, v45
	v_lshlrev_b32_e32 v68, 16, v46
	v_and_b32_e32 v69, 0xffff0000, v46
	v_lshlrev_b32_e32 v70, 16, v47
	v_and_b32_e32 v71, 0xffff0000, v47
	global_load_dwordx4 v[44:47], v[4:5], off offset:1984
	s_waitcnt lgkmcnt(2)
	v_mfma_f32_16x16x4_f32 v[8:11], v64, v56, v[8:11]
	v_mfma_f32_16x16x4_f32 v[8:11], v65, v57, v[8:11]
	v_mfma_f32_16x16x4_f32 v[8:11], v66, v58, v[8:11]
	v_mfma_f32_16x16x4_f32 v[8:11], v67, v59, v[8:11]
	v_mfma_f32_16x16x4_f32 v[8:11], v68, v60, v[8:11]
	v_mfma_f32_16x16x4_f32 v[8:11], v69, v61, v[8:11]
	v_mfma_f32_16x16x4_f32 v[8:11], v70, v62, v[8:11]
	v_mfma_f32_16x16x4_f32 v[8:11], v71, v63, v[8:11]
	ds_read_b128 v[56:59], v148 offset:25600
	ds_read_b128 v[60:63], v148 offset:25616
	s_waitcnt vmcnt(7)
	v_lshlrev_b32_e32 v64, 16, v16
	v_and_b32_e32 v65, 0xffff0000, v16
	v_lshlrev_b32_e32 v66, 16, v17
	v_and_b32_e32 v67, 0xffff0000, v17
	v_lshlrev_b32_e32 v68, 16, v18
	v_and_b32_e32 v69, 0xffff0000, v18
	v_lshlrev_b32_e32 v70, 16, v19
	v_and_b32_e32 v71, 0xffff0000, v19
	s_waitcnt lgkmcnt(2)
	v_mfma_f32_16x16x4_f32 v[8:11], v64, v48, v[8:11]
	v_mfma_f32_16x16x4_f32 v[8:11], v65, v49, v[8:11]
	v_mfma_f32_16x16x4_f32 v[8:11], v66, v50, v[8:11]
	v_mfma_f32_16x16x4_f32 v[8:11], v67, v51, v[8:11]
	v_mfma_f32_16x16x4_f32 v[8:11], v68, v52, v[8:11]
	v_mfma_f32_16x16x4_f32 v[8:11], v69, v53, v[8:11]
	v_mfma_f32_16x16x4_f32 v[8:11], v70, v54, v[8:11]
	v_mfma_f32_16x16x4_f32 v[8:11], v71, v55, v[8:11]
	ds_read_b128 v[48:51], v148 offset:26624
	ds_read_b128 v[52:55], v148 offset:26640
	s_waitcnt vmcnt(6)
	v_lshlrev_b32_e32 v64, 16, v20
	v_and_b32_e32 v65, 0xffff0000, v20
	v_lshlrev_b32_e32 v66, 16, v21
	v_and_b32_e32 v67, 0xffff0000, v21
	v_lshlrev_b32_e32 v68, 16, v22
	v_and_b32_e32 v69, 0xffff0000, v22
	v_lshlrev_b32_e32 v70, 16, v23
	v_and_b32_e32 v71, 0xffff0000, v23
	s_waitcnt lgkmcnt(2)
	v_mfma_f32_16x16x4_f32 v[8:11], v64, v56, v[8:11]
	v_mfma_f32_16x16x4_f32 v[8:11], v65, v57, v[8:11]
	v_mfma_f32_16x16x4_f32 v[8:11], v66, v58, v[8:11]
	v_mfma_f32_16x16x4_f32 v[8:11], v67, v59, v[8:11]
	v_mfma_f32_16x16x4_f32 v[8:11], v68, v60, v[8:11]
	v_mfma_f32_16x16x4_f32 v[8:11], v69, v61, v[8:11]
	v_mfma_f32_16x16x4_f32 v[8:11], v70, v62, v[8:11]
	v_mfma_f32_16x16x4_f32 v[8:11], v71, v63, v[8:11]
	ds_read_b128 v[56:59], v148 offset:27648
	ds_read_b128 v[60:63], v148 offset:27664
	s_waitcnt vmcnt(5)
	v_lshlrev_b32_e32 v64, 16, v24
	v_and_b32_e32 v65, 0xffff0000, v24
	v_lshlrev_b32_e32 v66, 16, v25
	v_and_b32_e32 v67, 0xffff0000, v25
	v_lshlrev_b32_e32 v68, 16, v26
	v_and_b32_e32 v69, 0xffff0000, v26
	v_lshlrev_b32_e32 v70, 16, v27
	v_and_b32_e32 v71, 0xffff0000, v27
	s_waitcnt lgkmcnt(2)
	v_mfma_f32_16x16x4_f32 v[8:11], v64, v48, v[8:11]
	v_mfma_f32_16x16x4_f32 v[8:11], v65, v49, v[8:11]
	v_mfma_f32_16x16x4_f32 v[8:11], v66, v50, v[8:11]
	v_mfma_f32_16x16x4_f32 v[8:11], v67, v51, v[8:11]
	v_mfma_f32_16x16x4_f32 v[8:11], v68, v52, v[8:11]
	v_mfma_f32_16x16x4_f32 v[8:11], v69, v53, v[8:11]
	v_mfma_f32_16x16x4_f32 v[8:11], v70, v54, v[8:11]
	v_mfma_f32_16x16x4_f32 v[8:11], v71, v55, v[8:11]
	ds_read_b128 v[48:51], v148 offset:28672
	ds_read_b128 v[52:55], v148 offset:28688
	s_waitcnt vmcnt(4)
	v_lshlrev_b32_e32 v64, 16, v28
	v_and_b32_e32 v65, 0xffff0000, v28
	v_lshlrev_b32_e32 v66, 16, v29
	v_and_b32_e32 v67, 0xffff0000, v29
	v_lshlrev_b32_e32 v68, 16, v30
	v_and_b32_e32 v69, 0xffff0000, v30
	v_lshlrev_b32_e32 v70, 16, v31
	v_and_b32_e32 v71, 0xffff0000, v31
	s_waitcnt lgkmcnt(2)
	v_mfma_f32_16x16x4_f32 v[8:11], v64, v56, v[8:11]
	v_mfma_f32_16x16x4_f32 v[8:11], v65, v57, v[8:11]
	v_mfma_f32_16x16x4_f32 v[8:11], v66, v58, v[8:11]
	v_mfma_f32_16x16x4_f32 v[8:11], v67, v59, v[8:11]
	v_mfma_f32_16x16x4_f32 v[8:11], v68, v60, v[8:11]
	v_mfma_f32_16x16x4_f32 v[8:11], v69, v61, v[8:11]
	v_mfma_f32_16x16x4_f32 v[8:11], v70, v62, v[8:11]
	v_mfma_f32_16x16x4_f32 v[8:11], v71, v63, v[8:11]
	ds_read_b128 v[56:59], v148 offset:29696
	ds_read_b128 v[60:63], v148 offset:29712
	s_waitcnt vmcnt(3)
	v_lshlrev_b32_e32 v64, 16, v32
	v_and_b32_e32 v65, 0xffff0000, v32
	v_lshlrev_b32_e32 v66, 16, v33
	v_and_b32_e32 v67, 0xffff0000, v33
	v_lshlrev_b32_e32 v68, 16, v34
	v_and_b32_e32 v69, 0xffff0000, v34
	v_lshlrev_b32_e32 v70, 16, v35
	v_and_b32_e32 v71, 0xffff0000, v35
	s_waitcnt lgkmcnt(2)
; #define SHX(v, m) shx_((v), (m), lane)
; __device__ void ba_item(const Params& p, int L, int rp) {
;     ...
;       _Pragma("unroll") for (int j = 0; j < 8; ++j) {
;         float s = 0.f;
;         _Pragma("unroll") for (int e4 = 0; e4 < 4; ++e4) _Pragma("unroll") for (int e = 0; e < 4; ++e) s += hf[e4 * 4 + e] * wr_[j][e4][e];
;         _Pragma("unroll") for (int o = 32; o >= 1; o >>= 1) s += SHX(s, o);
;         a[j] = s;
;       }
	v_mfma_f32_16x16x4_f32 v[8:11], v64, v48, v[8:11]
	v_mfma_f32_16x16x4_f32 v[8:11], v65, v49, v[8:11]
	v_mfma_f32_16x16x4_f32 v[8:11], v66, v50, v[8:11]
	v_mfma_f32_16x16x4_f32 v[8:11], v67, v51, v[8:11]
	v_mfma_f32_16x16x4_f32 v[8:11], v68, v52, v[8:11]
	v_mfma_f32_16x16x4_f32 v[8:11], v69, v53, v[8:11]
	v_mfma_f32_16x16x4_f32 v[8:11], v70, v54, v[8:11]
	v_mfma_f32_16x16x4_f32 v[8:11], v71, v55, v[8:11]
	ds_read_b128 v[48:51], v148 offset:30720
	ds_read_b128 v[52:55], v148 offset:30736
	s_waitcnt vmcnt(2)
	v_lshlrev_b32_e32 v64, 16, v36
	v_and_b32_e32 v65, 0xffff0000, v36
	v_lshlrev_b32_e32 v66, 16, v37
	v_and_b32_e32 v67, 0xffff0000, v37
	v_lshlrev_b32_e32 v68, 16, v38
	v_and_b32_e32 v69, 0xffff0000, v38
	v_lshlrev_b32_e32 v70, 16, v39
	v_and_b32_e32 v71, 0xffff0000, v39
	s_waitcnt lgkmcnt(2)
	v_mfma_f32_16x16x4_f32 v[8:11], v64, v56, v[8:11]
	v_mfma_f32_16x16x4_f32 v[8:11], v65, v57, v[8:11]
	v_mfma_f32_16x16x4_f32 v[8:11], v66, v58, v[8:11]
	v_mfma_f32_16x16x4_f32 v[8:11], v67, v59, v[8:11]
	v_mfma_f32_16x16x4_f32 v[8:11], v68, v60, v[8:11]
	v_mfma_f32_16x16x4_f32 v[8:11], v69, v61, v[8:11]
	v_mfma_f32_16x16x4_f32 v[8:11], v70, v62, v[8:11]
	v_mfma_f32_16x16x4_f32 v[8:11], v71, v63, v[8:11]
	ds_read_b128 v[56:59], v148 offset:31744
	ds_read_b128 v[60:63], v148 offset:31760
	s_waitcnt vmcnt(1)
	v_lshlrev_b32_e32 v64, 16, v40
	v_and_b32_e32 v65, 0xffff0000, v40
	v_lshlrev_b32_e32 v66, 16, v41
	v_and_b32_e32 v67, 0xffff0000, v41
	v_lshlrev_b32_e32 v68, 16, v42
	v_and_b32_e32 v69, 0xffff0000, v42
	v_lshlrev_b32_e32 v70, 16, v43
	v_and_b32_e32 v71, 0xffff0000, v43
	s_waitcnt lgkmcnt(2)
	v_mfma_f32_16x16x4_f32 v[8:11], v64, v48, v[8:11]
	v_mfma_f32_16x16x4_f32 v[8:11], v65, v49, v[8:11]
	v_mfma_f32_16x16x4_f32 v[8:11], v66, v50, v[8:11]
	v_mfma_f32_16x16x4_f32 v[8:11], v67, v51, v[8:11]
	v_mfma_f32_16x16x4_f32 v[8:11], v68, v52, v[8:11]
	v_mfma_f32_16x16x4_f32 v[8:11], v69, v53, v[8:11]
	v_mfma_f32_16x16x4_f32 v[8:11], v70, v54, v[8:11]
	v_mfma_f32_16x16x4_f32 v[8:11], v71, v55, v[8:11]
	s_waitcnt vmcnt(0)
	v_lshlrev_b32_e32 v64, 16, v44
	v_and_b32_e32 v65, 0xffff0000, v44
	v_lshlrev_b32_e32 v66, 16, v45
	v_and_b32_e32 v67, 0xffff0000, v45
	v_lshlrev_b32_e32 v68, 16, v46
	v_and_b32_e32 v69, 0xffff0000, v46
	v_lshlrev_b32_e32 v70, 16, v47
	v_and_b32_e32 v71, 0xffff0000, v47
	s_waitcnt lgkmcnt(0)
; __device__ __forceinline__ float fexp(float x) { return __builtin_amdgcn_exp2f(x * 1.4426950408889634f); }
; __device__ __forceinline__ float flog(float x) { return __builtin_amdgcn_logf(x) * 0.6931471805599453f; }
; __device__ __forceinline__ float frsq(float x) { return __builtin_amdgcn_rsqf(x); }
; __device__ __forceinline__ float sigmoidf_(float x) { return frcp(1.0f + fexp(-x)); }
; __device__ void ba_item(const Params& p, int L, int rp) {
;     ...
;       if (lane < 8) {
;         float s16 = 0.f;
;         _Pragma("unroll") for (int i = 0; i < 4; ++i) s16 += (ps[u][i][0] + ps[u][i][1]) + (ps[u][i][2] + ps[u][i][3]);
;         float rs = frsq(s16 * (1.0f / 1024.0f) + 1e-6f);
;         float v = 0.f;
;         _Pragma("unroll") for (int j = 0; j < 8; ++j) if (lane == j) v = a[j];
;         v *= rs;
;         float r;
;         if (lane < 4) r = sigmoidf_(v);
;         else {
;           int hh = lane - 4;
;           float z = v + p.dn_dt_bias[(L >> 1) * 4 + hh];
;           float sp = (z > 20.f) ? z : flog(1.0f + fexp(z));
;           r = -fexp(p.dn_a_log[(L >> 1) * 4 + hh]) * sp;
;         }
;         miscw[MF_BG + (long)row * 8 + lane] = r;
;       }
	v_mfma_f32_16x16x4_f32 v[8:11], v64, v56, v[8:11]
	v_mfma_f32_16x16x4_f32 v[8:11], v65, v57, v[8:11]
	v_mfma_f32_16x16x4_f32 v[8:11], v66, v58, v[8:11]
	v_mfma_f32_16x16x4_f32 v[8:11], v67, v59, v[8:11]
	v_mfma_f32_16x16x4_f32 v[8:11], v68, v60, v[8:11]
	v_mfma_f32_16x16x4_f32 v[8:11], v69, v61, v[8:11]
	v_mfma_f32_16x16x4_f32 v[8:11], v70, v62, v[8:11]
	v_mfma_f32_16x16x4_f32 v[8:11], v71, v63, v[8:11]
	v_cmp_gt_u32_e32 vcc, 8, v2
	s_and_saveexec_b64 s[12:13], vcc
	s_nop 4
	v_add_f32_e32 v72, v72, v73
	v_add_f32_e32 v74, v74, v75
	v_add_f32_e32 v72, v72, v74
	v_add_f32_e32 v76, v76, v77
	v_add_f32_e32 v78, v78, v79
	v_add_f32_e32 v76, v76, v78
	v_add_f32_e32 v80, v80, v81
	v_add_f32_e32 v82, v82, v83
	v_add_f32_e32 v80, v80, v82
	v_add_f32_e32 v84, v84, v85
	v_add_f32_e32 v86, v86, v87
	v_add_f32_e32 v84, v84, v86
	v_add_f32_e32 v72, 0, v72
	v_add_f32_e32 v72, v76, v72
	v_add_f32_e32 v72, v80, v72
	v_add_f32_e32 v72, v84, v72
	v_fmamk_f32 v72, v72, 0x3a800000, v201
	v_rsq_f32_e32 v72, v72
	s_nop 0
	v_mul_f32_e32 v144, v8, v72
	v_mul_f32_e32 v145, 0xbfb8aa3b, v144
	v_exp_f32_e32 v145, v145
	s_nop 0
	v_add_f32_e32 v145, 1.0, v145
	v_rcp_f32_e32 v145, v145
	v_add_f32_e32 v146, v144, v142
	v_mul_f32_e32 v147, 0x3fb8aa3b, v146
	v_exp_f32_e32 v147, v147
	v_cmp_lt_f32_e64 s[0:1], s57, v146
	v_add_f32_e32 v147, 1.0, v147
	v_log_f32_e32 v147, v147
	s_nop 0
	v_mul_f32_e32 v147, 0x3f317218, v147
	v_cndmask_b32_e64 v146, v147, v146, s[0:1]
	v_mul_f32_e32 v147, 0x3fb8aa3b, v143
	v_exp_f32_e32 v147, v147
	s_nop 0
	v_mul_f32_e64 v146, v146, -v147
	v_cmp_gt_u32_e64 s[0:1], 4, v138
	s_nop 1
	v_cndmask_b32_e64 v146, v146, v145, s[0:1]
	global_store_dword v[140:141], v146, off offset:0
	v_add_f32_e32 v88, v88, v89
	v_add_f32_e32 v90, v90, v91
	v_add_f32_e32 v88, v88, v90
	v_add_f32_e32 v92, v92, v93
	v_add_f32_e32 v94, v94, v95
	v_add_f32_e32 v92, v92, v94
	v_add_f32_e32 v96, v96, v97
	v_add_f32_e32 v98, v98, v99
	v_add_f32_e32 v96, v96, v98
	v_add_f32_e32 v100, v100, v101
	v_add_f32_e32 v102, v102, v103
	v_add_f32_e32 v100, v100, v102
	v_add_f32_e32 v88, 0, v88
	v_add_f32_e32 v88, v92, v88
	v_add_f32_e32 v88, v96, v88
	v_add_f32_e32 v88, v100, v88
	v_fmamk_f32 v88, v88, 0x3a800000, v201
	v_rsq_f32_e32 v88, v88
	s_nop 0
	v_mul_f32_e32 v144, v9, v88
	v_mul_f32_e32 v145, 0xbfb8aa3b, v144
	v_exp_f32_e32 v145, v145
	s_nop 0
	v_add_f32_e32 v145, 1.0, v145
	v_rcp_f32_e32 v145, v145
	v_add_f32_e32 v146, v144, v142
	v_mul_f32_e32 v147, 0x3fb8aa3b, v146
	v_exp_f32_e32 v147, v147
	v_cmp_lt_f32_e64 s[0:1], s57, v146
	v_add_f32_e32 v147, 1.0, v147
	v_log_f32_e32 v147, v147
	s_nop 0
	v_mul_f32_e32 v147, 0x3f317218, v147
	v_cndmask_b32_e64 v146, v147, v146, s[0:1]
	v_mul_f32_e32 v147, 0x3fb8aa3b, v143
	v_exp_f32_e32 v147, v147
	s_nop 0
	v_mul_f32_e64 v146, v146, -v147
	v_cmp_gt_u32_e64 s[0:1], 4, v138
	s_nop 1
	v_cndmask_b32_e64 v146, v146, v145, s[0:1]
	global_store_dword v[140:141], v146, off offset:32
	v_add_f32_e32 v104, v104, v105
	v_add_f32_e32 v106, v106, v107
	v_add_f32_e32 v104, v104, v106
	v_add_f32_e32 v108, v108, v109
	v_add_f32_e32 v110, v110, v111
	v_add_f32_e32 v108, v108, v110
	v_add_f32_e32 v112, v112, v113
	v_add_f32_e32 v114, v114, v115
	v_add_f32_e32 v112, v112, v114
	v_add_f32_e32 v116, v116, v117
	v_add_f32_e32 v118, v118, v119
	v_add_f32_e32 v116, v116, v118
	v_add_f32_e32 v104, 0, v104
	v_add_f32_e32 v104, v108, v104
	v_add_f32_e32 v104, v112, v104
	v_add_f32_e32 v104, v116, v104
	v_fmamk_f32 v104, v104, 0x3a800000, v201
	v_rsq_f32_e32 v104, v104
	s_nop 0
	v_mul_f32_e32 v144, v10, v104
	v_mul_f32_e32 v145, 0xbfb8aa3b, v144
	v_exp_f32_e32 v145, v145
	s_nop 0
	v_add_f32_e32 v145, 1.0, v145
	v_rcp_f32_e32 v145, v145
	v_add_f32_e32 v146, v144, v142
	v_mul_f32_e32 v147, 0x3fb8aa3b, v146
	v_exp_f32_e32 v147, v147
	v_cmp_lt_f32_e64 s[0:1], s57, v146
	v_add_f32_e32 v147, 1.0, v147
	v_log_f32_e32 v147, v147
	s_nop 0
	v_mul_f32_e32 v147, 0x3f317218, v147
	v_cndmask_b32_e64 v146, v147, v146, s[0:1]
	v_mul_f32_e32 v147, 0x3fb8aa3b, v143
	v_exp_f32_e32 v147, v147
	s_nop 0
	v_mul_f32_e64 v146, v146, -v147
	v_cmp_gt_u32_e64 s[0:1], 4, v138
	s_nop 1
	v_cndmask_b32_e64 v146, v146, v145, s[0:1]
	global_store_dword v[140:141], v146, off offset:64
	v_add_f32_e32 v120, v120, v121
	v_add_f32_e32 v122, v122, v123
	v_add_f32_e32 v120, v120, v122
	v_add_f32_e32 v124, v124, v125
	v_add_f32_e32 v126, v126, v127
	v_add_f32_e32 v124, v124, v126
	v_add_f32_e32 v128, v128, v129
	v_add_f32_e32 v130, v130, v131
	v_add_f32_e32 v128, v128, v130
	v_add_f32_e32 v132, v132, v133
	v_add_f32_e32 v134, v134, v135
	v_add_f32_e32 v132, v132, v134
	v_add_f32_e32 v120, 0, v120
	v_add_f32_e32 v120, v124, v120
	v_add_f32_e32 v120, v128, v120
	v_add_f32_e32 v120, v132, v120
	v_fmamk_f32 v120, v120, 0x3a800000, v201
	v_rsq_f32_e32 v120, v120
	s_nop 0
	v_mul_f32_e32 v144, v11, v120
	v_mul_f32_e32 v145, 0xbfb8aa3b, v144
	v_exp_f32_e32 v145, v145
	s_nop 0
	v_add_f32_e32 v145, 1.0, v145
	v_rcp_f32_e32 v145, v145
	v_add_f32_e32 v146, v144, v142
	v_mul_f32_e32 v147, 0x3fb8aa3b, v146
	v_exp_f32_e32 v147, v147
	v_cmp_lt_f32_e64 s[0:1], s57, v146
	v_add_f32_e32 v147, 1.0, v147
	v_log_f32_e32 v147, v147
	s_nop 0
	v_mul_f32_e32 v147, 0x3f317218, v147
	v_cndmask_b32_e64 v146, v147, v146, s[0:1]
	v_mul_f32_e32 v147, 0x3fb8aa3b, v143
	v_exp_f32_e32 v147, v147
	s_nop 0
	v_mul_f32_e64 v146, v146, -v147
	v_cmp_gt_u32_e64 s[0:1], 4, v138
	s_nop 1
	v_cndmask_b32_e64 v146, v146, v145, s[0:1]
	global_store_dword v[140:141], v146, off offset:96
	s_or_b64 exec, exec, s[12:13]
	s_barrier
	s_branch .LBB0_627
